# C18: C12 + cm_w_s bf16 copy loop issues its 16 loads together (was one load per round trip)
# baseline (speedup 1.0000x reference)
.LBB0_68:
	global_load_dwordx4 v[100:103], v[24:25], off
	v_lshl_add_u64 v[24:25], v[24:25], 0, s[28:29]
	global_load_dwordx4 v[104:107], v[24:25], off
	v_lshl_add_u64 v[24:25], v[24:25], 0, s[28:29]
	global_load_dwordx4 v[108:111], v[24:25], off
	v_lshl_add_u64 v[24:25], v[24:25], 0, s[28:29]
	global_load_dwordx4 v[112:115], v[24:25], off
	v_lshl_add_u64 v[24:25], v[24:25], 0, s[28:29]
	global_load_dwordx4 v[116:119], v[24:25], off
	v_lshl_add_u64 v[24:25], v[24:25], 0, s[28:29]
	global_load_dwordx4 v[120:123], v[24:25], off
	v_lshl_add_u64 v[24:25], v[24:25], 0, s[28:29]
	global_load_dwordx4 v[124:127], v[24:25], off
	v_lshl_add_u64 v[24:25], v[24:25], 0, s[28:29]
	global_load_dwordx4 v[128:131], v[24:25], off
	v_lshl_add_u64 v[24:25], v[24:25], 0, s[28:29]
	global_load_dwordx4 v[132:135], v[24:25], off
	v_lshl_add_u64 v[24:25], v[24:25], 0, s[28:29]
	global_load_dwordx4 v[144:147], v[24:25], off
	v_lshl_add_u64 v[24:25], v[24:25], 0, s[28:29]
	global_load_dwordx4 v[148:151], v[24:25], off
	v_lshl_add_u64 v[24:25], v[24:25], 0, s[28:29]
	global_load_dwordx4 v[152:155], v[24:25], off
	v_lshl_add_u64 v[24:25], v[24:25], 0, s[28:29]
	global_load_dwordx4 v[156:159], v[24:25], off
	v_lshl_add_u64 v[24:25], v[24:25], 0, s[28:29]
	global_load_dwordx4 v[160:163], v[24:25], off
	v_lshl_add_u64 v[24:25], v[24:25], 0, s[28:29]
	global_load_dwordx4 v[164:167], v[24:25], off
	v_lshl_add_u64 v[24:25], v[24:25], 0, s[28:29]
	global_load_dwordx4 v[168:171], v[24:25], off
	v_lshl_add_u64 v[24:25], v[24:25], 0, s[28:29]
	s_waitcnt vmcnt(15)
	v_cvt_pk_bf16_f32 v100, v100, v101
	v_cvt_pk_bf16_f32 v101, v102, v103
	s_waitcnt vmcnt(14)
	v_cvt_pk_bf16_f32 v104, v104, v105
	v_cvt_pk_bf16_f32 v105, v106, v107
	s_waitcnt vmcnt(13)
	v_cvt_pk_bf16_f32 v108, v108, v109
	v_cvt_pk_bf16_f32 v109, v110, v111
	s_waitcnt vmcnt(12)
	v_cvt_pk_bf16_f32 v112, v112, v113
	v_cvt_pk_bf16_f32 v113, v114, v115
	s_waitcnt vmcnt(11)
	v_cvt_pk_bf16_f32 v116, v116, v117
	v_cvt_pk_bf16_f32 v117, v118, v119
	s_waitcnt vmcnt(10)
	v_cvt_pk_bf16_f32 v120, v120, v121
	v_cvt_pk_bf16_f32 v121, v122, v123
	s_waitcnt vmcnt(9)
	v_cvt_pk_bf16_f32 v124, v124, v125
	v_cvt_pk_bf16_f32 v125, v126, v127
	s_waitcnt vmcnt(8)
	v_cvt_pk_bf16_f32 v128, v128, v129
	v_cvt_pk_bf16_f32 v129, v130, v131
	s_waitcnt vmcnt(7)
	v_cvt_pk_bf16_f32 v132, v132, v133
	v_cvt_pk_bf16_f32 v133, v134, v135
	s_waitcnt vmcnt(6)
	v_cvt_pk_bf16_f32 v144, v144, v145
	v_cvt_pk_bf16_f32 v145, v146, v147
	s_waitcnt vmcnt(5)
	v_cvt_pk_bf16_f32 v148, v148, v149
	v_cvt_pk_bf16_f32 v149, v150, v151
	s_waitcnt vmcnt(4)
	v_cvt_pk_bf16_f32 v152, v152, v153
	v_cvt_pk_bf16_f32 v153, v154, v155
	s_waitcnt vmcnt(3)
	v_cvt_pk_bf16_f32 v156, v156, v157
	v_cvt_pk_bf16_f32 v157, v158, v159
	s_waitcnt vmcnt(2)
	v_cvt_pk_bf16_f32 v160, v160, v161
	v_cvt_pk_bf16_f32 v161, v162, v163
	s_waitcnt vmcnt(1)
	v_cvt_pk_bf16_f32 v164, v164, v165
	v_cvt_pk_bf16_f32 v165, v166, v167
	s_waitcnt vmcnt(0)
	v_cvt_pk_bf16_f32 v168, v168, v169
	v_cvt_pk_bf16_f32 v169, v170, v171
	global_store_dwordx2 v[22:23], v[100:101], off
	v_lshl_add_u64 v[22:23], v[22:23], 0, s[20:21]
	global_store_dwordx2 v[22:23], v[104:105], off
	v_lshl_add_u64 v[22:23], v[22:23], 0, s[20:21]
	global_store_dwordx2 v[22:23], v[108:109], off
	v_lshl_add_u64 v[22:23], v[22:23], 0, s[20:21]
	global_store_dwordx2 v[22:23], v[112:113], off
	v_lshl_add_u64 v[22:23], v[22:23], 0, s[20:21]
	global_store_dwordx2 v[22:23], v[116:117], off
	v_lshl_add_u64 v[22:23], v[22:23], 0, s[20:21]
	global_store_dwordx2 v[22:23], v[120:121], off
	v_lshl_add_u64 v[22:23], v[22:23], 0, s[20:21]
	global_store_dwordx2 v[22:23], v[124:125], off
	v_lshl_add_u64 v[22:23], v[22:23], 0, s[20:21]
	global_store_dwordx2 v[22:23], v[128:129], off
	v_lshl_add_u64 v[22:23], v[22:23], 0, s[20:21]
	global_store_dwordx2 v[22:23], v[132:133], off
	v_lshl_add_u64 v[22:23], v[22:23], 0, s[20:21]
	global_store_dwordx2 v[22:23], v[144:145], off
	v_lshl_add_u64 v[22:23], v[22:23], 0, s[20:21]
	global_store_dwordx2 v[22:23], v[148:149], off
	v_lshl_add_u64 v[22:23], v[22:23], 0, s[20:21]
	global_store_dwordx2 v[22:23], v[152:153], off
	v_lshl_add_u64 v[22:23], v[22:23], 0, s[20:21]
	global_store_dwordx2 v[22:23], v[156:157], off
	v_lshl_add_u64 v[22:23], v[22:23], 0, s[20:21]
	global_store_dwordx2 v[22:23], v[160:161], off
	v_lshl_add_u64 v[22:23], v[22:23], 0, s[20:21]
	global_store_dwordx2 v[22:23], v[164:165], off
	v_lshl_add_u64 v[22:23], v[22:23], 0, s[20:21]
	global_store_dwordx2 v[22:23], v[168:169], off
	v_lshl_add_u64 v[22:23], v[22:23], 0, s[20:21]
	s_or_b64 exec, exec, s[2:3]
	s_mov_b64 s[2:3], 0

.LBB0_774:
	global_load_dwordx4 v[100:103], v[24:25], off
	v_lshl_add_u64 v[24:25], v[24:25], 0, s[26:27]
	global_load_dwordx4 v[104:107], v[24:25], off
	v_lshl_add_u64 v[24:25], v[24:25], 0, s[26:27]
	global_load_dwordx4 v[108:111], v[24:25], off
	v_lshl_add_u64 v[24:25], v[24:25], 0, s[26:27]
	global_load_dwordx4 v[112:115], v[24:25], off
	v_lshl_add_u64 v[24:25], v[24:25], 0, s[26:27]
	global_load_dwordx4 v[116:119], v[24:25], off
	v_lshl_add_u64 v[24:25], v[24:25], 0, s[26:27]
	global_load_dwordx4 v[120:123], v[24:25], off
	v_lshl_add_u64 v[24:25], v[24:25], 0, s[26:27]
	global_load_dwordx4 v[124:127], v[24:25], off
	v_lshl_add_u64 v[24:25], v[24:25], 0, s[26:27]
	global_load_dwordx4 v[128:131], v[24:25], off
	v_lshl_add_u64 v[24:25], v[24:25], 0, s[26:27]
	global_load_dwordx4 v[132:135], v[24:25], off
	v_lshl_add_u64 v[24:25], v[24:25], 0, s[26:27]
	global_load_dwordx4 v[144:147], v[24:25], off
	v_lshl_add_u64 v[24:25], v[24:25], 0, s[26:27]
	global_load_dwordx4 v[148:151], v[24:25], off
	v_lshl_add_u64 v[24:25], v[24:25], 0, s[26:27]
	global_load_dwordx4 v[152:155], v[24:25], off
	v_lshl_add_u64 v[24:25], v[24:25], 0, s[26:27]
	global_load_dwordx4 v[156:159], v[24:25], off
	v_lshl_add_u64 v[24:25], v[24:25], 0, s[26:27]
	global_load_dwordx4 v[160:163], v[24:25], off
	v_lshl_add_u64 v[24:25], v[24:25], 0, s[26:27]
	global_load_dwordx4 v[164:167], v[24:25], off
	v_lshl_add_u64 v[24:25], v[24:25], 0, s[26:27]
	global_load_dwordx4 v[168:171], v[24:25], off
	v_lshl_add_u64 v[24:25], v[24:25], 0, s[26:27]
	s_waitcnt vmcnt(15)
	v_cvt_pk_bf16_f32 v100, v100, v101
	v_cvt_pk_bf16_f32 v101, v102, v103
	s_waitcnt vmcnt(14)
	v_cvt_pk_bf16_f32 v104, v104, v105
	v_cvt_pk_bf16_f32 v105, v106, v107
	s_waitcnt vmcnt(13)
	v_cvt_pk_bf16_f32 v108, v108, v109
	v_cvt_pk_bf16_f32 v109, v110, v111
	s_waitcnt vmcnt(12)
	v_cvt_pk_bf16_f32 v112, v112, v113
	v_cvt_pk_bf16_f32 v113, v114, v115
	s_waitcnt vmcnt(11)
	v_cvt_pk_bf16_f32 v116, v116, v117
	v_cvt_pk_bf16_f32 v117, v118, v119
	s_waitcnt vmcnt(10)
	v_cvt_pk_bf16_f32 v120, v120, v121
	v_cvt_pk_bf16_f32 v121, v122, v123
	s_waitcnt vmcnt(9)
	v_cvt_pk_bf16_f32 v124, v124, v125
	v_cvt_pk_bf16_f32 v125, v126, v127
	s_waitcnt vmcnt(8)
	v_cvt_pk_bf16_f32 v128, v128, v129
	v_cvt_pk_bf16_f32 v129, v130, v131
	s_waitcnt vmcnt(7)
	v_cvt_pk_bf16_f32 v132, v132, v133
	v_cvt_pk_bf16_f32 v133, v134, v135
	s_waitcnt vmcnt(6)
	v_cvt_pk_bf16_f32 v144, v144, v145
	v_cvt_pk_bf16_f32 v145, v146, v147
	s_waitcnt vmcnt(5)
	v_cvt_pk_bf16_f32 v148, v148, v149
	v_cvt_pk_bf16_f32 v149, v150, v151
	s_waitcnt vmcnt(4)
	v_cvt_pk_bf16_f32 v152, v152, v153
	v_cvt_pk_bf16_f32 v153, v154, v155
	s_waitcnt vmcnt(3)
	v_cvt_pk_bf16_f32 v156, v156, v157
	v_cvt_pk_bf16_f32 v157, v158, v159
	s_waitcnt vmcnt(2)
	v_cvt_pk_bf16_f32 v160, v160, v161
	v_cvt_pk_bf16_f32 v161, v162, v163
	s_waitcnt vmcnt(1)
	v_cvt_pk_bf16_f32 v164, v164, v165
	v_cvt_pk_bf16_f32 v165, v166, v167
	s_waitcnt vmcnt(0)
	v_cvt_pk_bf16_f32 v168, v168, v169
	v_cvt_pk_bf16_f32 v169, v170, v171
	global_store_dwordx2 v[22:23], v[100:101], off
	v_lshl_add_u64 v[22:23], v[22:23], 0, s[20:21]
	global_store_dwordx2 v[22:23], v[104:105], off
	v_lshl_add_u64 v[22:23], v[22:23], 0, s[20:21]
	global_store_dwordx2 v[22:23], v[108:109], off
	v_lshl_add_u64 v[22:23], v[22:23], 0, s[20:21]
	global_store_dwordx2 v[22:23], v[112:113], off
	v_lshl_add_u64 v[22:23], v[22:23], 0, s[20:21]
	global_store_dwordx2 v[22:23], v[116:117], off
	v_lshl_add_u64 v[22:23], v[22:23], 0, s[20:21]
	global_store_dwordx2 v[22:23], v[120:121], off
	v_lshl_add_u64 v[22:23], v[22:23], 0, s[20:21]
	global_store_dwordx2 v[22:23], v[124:125], off
	v_lshl_add_u64 v[22:23], v[22:23], 0, s[20:21]
	global_store_dwordx2 v[22:23], v[128:129], off
	v_lshl_add_u64 v[22:23], v[22:23], 0, s[20:21]
	global_store_dwordx2 v[22:23], v[132:133], off
	v_lshl_add_u64 v[22:23], v[22:23], 0, s[20:21]
	global_store_dwordx2 v[22:23], v[144:145], off
	v_lshl_add_u64 v[22:23], v[22:23], 0, s[20:21]
	global_store_dwordx2 v[22:23], v[148:149], off
	v_lshl_add_u64 v[22:23], v[22:23], 0, s[20:21]
	global_store_dwordx2 v[22:23], v[152:153], off
	v_lshl_add_u64 v[22:23], v[22:23], 0, s[20:21]
	global_store_dwordx2 v[22:23], v[156:157], off
	v_lshl_add_u64 v[22:23], v[22:23], 0, s[20:21]
	global_store_dwordx2 v[22:23], v[160:161], off
	v_lshl_add_u64 v[22:23], v[22:23], 0, s[20:21]
	global_store_dwordx2 v[22:23], v[164:165], off
	v_lshl_add_u64 v[22:23], v[22:23], 0, s[20:21]
	global_store_dwordx2 v[22:23], v[168:169], off
	v_lshl_add_u64 v[22:23], v[22:23], 0, s[20:21]
	s_or_b64 exec, exec, s[2:3]
	s_mov_b64 s[2:3], 0
